# stick-breaking units: gate loads of the epilogue issued at the start of the last tile into idle staging registers (plus queue-index prefetch)
# baseline (speedup 1.0000x reference)
; #define SLOAD(k0) do { _Pragma("unroll") for (int j_ = 0; j_ < 4; ++j_) { sv[j_] = *(const bf16x8*)(a.V + (size_t)((k0) + sr + 16 * j_) * a.kvstride + sc); \
;         sk[j_] = *(const bf16x8*)(a.K + (size_t)((k0) + sr + 16 * j_) * a.kvstride + sc); } } while (0)
; template <int MODE> ...
;     ...
;     for (int j = 0; j < nt; ++j) {
;         const int cur = j & 1, t = (MODE == 0) ? nt - 1 - j : j;
;         if (j + 1 < nt) { const int tn = (MODE == 0) ? t - 1 : t + 1; SLOAD(tn * 64); }
;         const bool active = (MODE == 1) || (t * 64 < qmax_w);
;     ...
;         const int row = wid * 32 + (lane >> 1), c0 = (lane & 1) * 64;
;         if (row < a.nvalid) {
;             const bf16_t* gp = a.gate + (size_t)row * a.gstride + c0; bf16_t* op = a.out + (size_t)row * a.ostride + c0;
;             u32x4 gv[8];
; #pragma unroll
;             for (int j = 0; j < 8; ++j) gv[j] = *(const u32x4*)(gp + 8 * j);
.LBB0_871:
	s_add_u32 s12, s74, s77
	s_addc_u32 s13, s75, 0
	s_add_u32 s12, s12, 0x1800
	s_addc_u32 s13, s13, 0
	v_lshrrev_b32_e32 v84, 1, v196
	v_or_b32_e32 v84, s76, v84
	v_mov_b64_e32 v[86:87], s[12:13]
	v_lshlrev_b32_e32 v88, 7, v195
	v_mad_i64_i32 v[86:87], s[14:15], v84, s55, v[86:87]
	v_and_b32_e32 v88, 0x80, v88
	v_mov_b32_e32 v89, 0
	s_nop 0
	v_lshl_add_u64 v[86:87], v[86:87], 0, v[88:89]
	global_load_dwordx4 v[132:135], v[86:87], off
	global_load_dwordx4 v[136:139], v[86:87], off offset:16
	global_load_dwordx4 v[140:143], v[86:87], off offset:32
	global_load_dwordx4 v[144:147], v[86:87], off offset:48
	global_load_dwordx4 v[148:151], v[86:87], off offset:64
	global_load_dwordx4 v[152:155], v[86:87], off offset:80
	global_load_dwordx4 v[156:159], v[86:87], off offset:96
	global_load_dwordx4 v[160:163], v[86:87], off offset:112
	s_and_b32 s86, s8, 1
	s_cmp_ge_i32 s10, s84
	s_cbranch_scc1 .LBB0_862

; #define LAS __attribute__((address_space(3)))
; __device__ __forceinline__ bf16_t f2bf(float f) { return (bf16_t)(cvtpk(f, 0.f) & 0xffffu); }
; __device__ __forceinline__ int crow(int r, int hi) { return (r & 3) + 8 * (r >> 2) + 4 * hi; }
; template <int MODE> ...
;     ...
;     LAS unsigned char* ost = lds + wid * (32 * 272);
; #pragma unroll
;     for (int r = 0; r < 16; ++r)
; #pragma unroll
;         for (int d0 = 0; d0 < 4; ++d0) { float v = o[d0][r]; if (MODE == 1) v *= rl[r];
;             *(LAS bf16_t*)(ost + crow(r, hi) * 272 + (d0 * 32 + r32) * 2) = f2bf(v); }
;     asm volatile("s_waitcnt lgkmcnt(0)" ::: "memory");
;     {
;         const int row = wid * 32 + (lane >> 1), c0 = (lane & 1) * 64;
;         if (row < a.nvalid) {
.LBB0_881:
	s_mulk_i32 s79, 0x2200
	s_add_i32 s6, s79, 0
	v_lshlrev_b32_e32 v1, 1, v197
	v_mul_u32_u24_e32 v2, 0x440, v198
	v_add3_u32 v1, s6, v1, v2
	v_cvt_pk_bf16_f32 v2, v52, v3
	ds_write_b16 v1, v2
	v_cvt_pk_bf16_f32 v2, v36, v3
	ds_write_b16 v1, v2 offset:64
	v_cvt_pk_bf16_f32 v2, v20, v3
	ds_write_b16 v1, v2 offset:128
	v_cvt_pk_bf16_f32 v2, v4, v3
	ds_write_b16 v1, v2 offset:192
	v_cvt_pk_bf16_f32 v2, v53, v3
	ds_write_b16 v1, v2 offset:272
	v_cvt_pk_bf16_f32 v2, v37, v3
	ds_write_b16 v1, v2 offset:336
	v_cvt_pk_bf16_f32 v2, v21, v3
	ds_write_b16 v1, v2 offset:400
	v_cvt_pk_bf16_f32 v2, v5, v3
	ds_write_b16 v1, v2 offset:464
	v_cvt_pk_bf16_f32 v2, v54, v3
	ds_write_b16 v1, v2 offset:544
	v_cvt_pk_bf16_f32 v2, v38, v3
	ds_write_b16 v1, v2 offset:608
	v_cvt_pk_bf16_f32 v2, v22, v3
	ds_write_b16 v1, v2 offset:672
	v_cvt_pk_bf16_f32 v2, v6, v3
	ds_write_b16 v1, v2 offset:736
	v_cvt_pk_bf16_f32 v2, v55, v3
	ds_write_b16 v1, v2 offset:816
	v_cvt_pk_bf16_f32 v2, v39, v3
	ds_write_b16 v1, v2 offset:880
	v_cvt_pk_bf16_f32 v2, v23, v3
	ds_write_b16 v1, v2 offset:944
	v_cvt_pk_bf16_f32 v2, v7, v3
	ds_write_b16 v1, v2 offset:1008
	v_cvt_pk_bf16_f32 v2, v56, v3
	ds_write_b16 v1, v2 offset:2176
	v_cvt_pk_bf16_f32 v2, v40, v3
	ds_write_b16 v1, v2 offset:2240
	v_cvt_pk_bf16_f32 v2, v24, v3
	ds_write_b16 v1, v2 offset:2304
	v_cvt_pk_bf16_f32 v2, v8, v3
	ds_write_b16 v1, v2 offset:2368
	v_cvt_pk_bf16_f32 v2, v57, v3
	ds_write_b16 v1, v2 offset:2448
	v_cvt_pk_bf16_f32 v2, v41, v3
	ds_write_b16 v1, v2 offset:2512
	v_cvt_pk_bf16_f32 v2, v25, v3
	ds_write_b16 v1, v2 offset:2576
	v_cvt_pk_bf16_f32 v2, v9, v3
	ds_write_b16 v1, v2 offset:2640
	v_cvt_pk_bf16_f32 v2, v58, v3
	ds_write_b16 v1, v2 offset:2720
	v_cvt_pk_bf16_f32 v2, v42, v3
	ds_write_b16 v1, v2 offset:2784
	v_cvt_pk_bf16_f32 v2, v26, v3
	ds_write_b16 v1, v2 offset:2848
	v_cvt_pk_bf16_f32 v2, v10, v3
	ds_write_b16 v1, v2 offset:2912
	v_cvt_pk_bf16_f32 v2, v59, v3
	ds_write_b16 v1, v2 offset:2992
	v_cvt_pk_bf16_f32 v2, v43, v3
	ds_write_b16 v1, v2 offset:3056
	v_cvt_pk_bf16_f32 v2, v27, v3
	ds_write_b16 v1, v2 offset:3120
	v_cvt_pk_bf16_f32 v2, v11, v3
	ds_write_b16 v1, v2 offset:3184
	v_cvt_pk_bf16_f32 v2, v60, v3
	ds_write_b16 v1, v2 offset:4352
	v_cvt_pk_bf16_f32 v2, v44, v3
	ds_write_b16 v1, v2 offset:4416
	v_cvt_pk_bf16_f32 v2, v28, v3
	ds_write_b16 v1, v2 offset:4480
	v_cvt_pk_bf16_f32 v2, v12, v3
	ds_write_b16 v1, v2 offset:4544
	v_cvt_pk_bf16_f32 v2, v61, v3
	ds_write_b16 v1, v2 offset:4624
	v_cvt_pk_bf16_f32 v2, v45, v3
	ds_write_b16 v1, v2 offset:4688
	v_cvt_pk_bf16_f32 v2, v29, v3
	ds_write_b16 v1, v2 offset:4752
	v_cvt_pk_bf16_f32 v2, v13, v3
	ds_write_b16 v1, v2 offset:4816
	v_cvt_pk_bf16_f32 v2, v62, v3
	ds_write_b16 v1, v2 offset:4896
	v_cvt_pk_bf16_f32 v2, v46, v3
	ds_write_b16 v1, v2 offset:4960
	v_cvt_pk_bf16_f32 v2, v30, v3
	ds_write_b16 v1, v2 offset:5024
	v_cvt_pk_bf16_f32 v2, v14, v3
	ds_write_b16 v1, v2 offset:5088
	v_cvt_pk_bf16_f32 v2, v63, v3
	ds_write_b16 v1, v2 offset:5168
	v_cvt_pk_bf16_f32 v2, v47, v3
	ds_write_b16 v1, v2 offset:5232
	v_cvt_pk_bf16_f32 v2, v31, v3
	ds_write_b16 v1, v2 offset:5296
	v_cvt_pk_bf16_f32 v2, v15, v3
	ds_write_b16 v1, v2 offset:5360
	v_cvt_pk_bf16_f32 v2, v64, v3
	ds_write_b16 v1, v2 offset:6528
	v_cvt_pk_bf16_f32 v2, v48, v3
	ds_write_b16 v1, v2 offset:6592
	v_cvt_pk_bf16_f32 v2, v32, v3
	ds_write_b16 v1, v2 offset:6656
	v_cvt_pk_bf16_f32 v2, v16, v3
	ds_write_b16 v1, v2 offset:6720
	v_cvt_pk_bf16_f32 v2, v65, v3
	ds_write_b16 v1, v2 offset:6800
	v_cvt_pk_bf16_f32 v2, v49, v3
	ds_write_b16 v1, v2 offset:6864
	v_cvt_pk_bf16_f32 v2, v33, v3
	ds_write_b16 v1, v2 offset:6928
	v_cvt_pk_bf16_f32 v2, v17, v3
	ds_write_b16 v1, v2 offset:6992
	v_cvt_pk_bf16_f32 v2, v66, v3
	ds_write_b16 v1, v2 offset:7072
	v_cvt_pk_bf16_f32 v2, v50, v3
	ds_write_b16 v1, v2 offset:7136
	v_cvt_pk_bf16_f32 v2, v34, v3
	ds_write_b16 v1, v2 offset:7200
	v_cvt_pk_bf16_f32 v2, v18, v3
	ds_write_b16 v1, v2 offset:7264
	v_cvt_pk_bf16_f32 v2, v67, v3
	ds_write_b16 v1, v2 offset:7344
	v_cvt_pk_bf16_f32 v2, v51, v3
	ds_write_b16 v1, v2 offset:7408
	v_cvt_pk_bf16_f32 v2, v35, v3
	ds_write_b16 v1, v2 offset:7472
	v_cvt_pk_bf16_f32 v2, v19, v3
	ds_write_b16 v1, v2 offset:7536
	s_waitcnt lgkmcnt(0)
	v_lshrrev_b32_e32 v1, 1, v196
	v_or_b32_e32 v4, s76, v1
	v_cmp_gt_i32_e32 vcc, s66, v4
	s_and_saveexec_b64 s[4:5], vcc
	s_cbranch_execz .LBB0_837
; #define LAS __attribute__((address_space(3)))
; __device__ __forceinline__ unsigned cvtpk(float lo, float hi) { unsigned r; asm volatile("v_cvt_pk_bf16_f32 %0, %1, %2" : "=v"(r) : "v"(lo), "v"(hi)); return r; }
; __device__ __forceinline__ float bf_lo(unsigned w) { return __uint_as_float(w << 16); }
; __device__ __forceinline__ float bf_hi(unsigned w) { return __uint_as_float(w & 0xffff0000u); }
; __device__ __forceinline__ float fast_exp2(float x) { return __builtin_amdgcn_exp2f(x); }
; __device__ __forceinline__ float fast_rcp(float x) { return __builtin_amdgcn_rcpf(x); }
; __device__ __forceinline__ float silu_f(float x) { return x * fast_rcp(1.f + fast_exp2(-x * LOG2E)); }
; template <int MODE> ...
;     ...
;         const int row = wid * 32 + (lane >> 1), c0 = (lane & 1) * 64;
;         if (row < a.nvalid) {
;             const bf16_t* gp = a.gate + (size_t)row * a.gstride + c0; bf16_t* op = a.out + (size_t)row * a.ostride + c0;
;             u32x4 gv[8];
; #pragma unroll
;             for (int j = 0; j < 8; ++j) gv[j] = *(const u32x4*)(gp + 8 * j);
; #pragma unroll
;             for (int j = 0; j < 8; ++j) { const u32x4 ov = *(const LAS u32x4*)(ost + (lane >> 1) * 272 + (c0 + 8 * j) * 2); u32x4 w;
; #pragma unroll
;                 for (int e = 0; e < 4; ++e) w[e] = cvtpk(bf_lo(ov[e]) * silu_f(bf_lo(gv[j][e])), bf_hi(ov[e]) * silu_f(bf_hi(gv[j][e])));
;                 *(u32x4*)(op + 8 * j) = w; }
	s_add_u32 s7, s74, s77
	s_addc_u32 s9, s75, 0
	s_add_u32 s8, s7, 0x1800
	s_addc_u32 s9, s9, 0
	v_mov_b64_e32 v[6:7], s[8:9]
	v_lshlrev_b32_e32 v2, 7, v195
	v_mad_i64_i32 v[6:7], s[8:9], v4, s55, v[6:7]
	v_and_b32_e32 v2, 0x80, v2
	v_lshl_add_u64 v[16:17], v[6:7], 0, v[2:3]
	s_waitcnt vmcnt(0)
	v_mov_b64_e32 v[30:31], v[132:133]
	v_mov_b64_e32 v[32:33], v[134:135]
	v_mov_b64_e32 v[34:35], v[136:137]
	v_mov_b64_e32 v[36:37], v[138:139]
	v_mul_u32_u24_e32 v1, 0x110, v1
	v_ashrrev_i32_e32 v5, 31, v4
	v_add3_u32 v1, s6, v1, v2
	v_lshlrev_b64 v[28:29], 12, v[4:5]
	ds_read_b128 v[38:41], v1
	v_mov_b64_e32 v[20:21], v[144:145]
	v_mov_b64_e32 v[22:23], v[146:147]
	v_mov_b64_e32 v[24:25], v[140:141]
	v_mov_b64_e32 v[26:27], v[142:143]
	v_mov_b64_e32 v[4:5], v[160:161]
	v_mov_b64_e32 v[6:7], v[162:163]
	v_mov_b64_e32 v[8:9], v[156:157]
	v_mov_b64_e32 v[10:11], v[158:159]
	v_mov_b64_e32 v[12:13], v[152:153]
	v_mov_b64_e32 v[14:15], v[154:155]
	v_mov_b64_e32 v[16:17], v[148:149]
	v_mov_b64_e32 v[18:19], v[150:151]
	s_lshl_b64 s[6:7], s[44:45], 12
	s_add_u32 s6, s33, s6
	s_addc_u32 s7, s52, s7
	s_add_u32 s6, s6, s77
	s_addc_u32 s7, s7, 0
	v_lshl_add_u64 v[28:29], s[6:7], 0, v[28:29]
	v_lshl_add_u64 v[28:29], v[28:29], 0, v[2:3]
	s_waitcnt lgkmcnt(0)
	v_lshlrev_b32_e32 v42, 16, v38
	v_and_b32_e32 v38, 0xffff0000, v38
	v_lshlrev_b32_e32 v43, 16, v39
	v_and_b32_e32 v39, 0xffff0000, v39
	v_lshlrev_b32_e32 v44, 16, v40
	v_and_b32_e32 v40, 0xffff0000, v40
	v_lshlrev_b32_e32 v45, 16, v41
	v_and_b32_e32 v41, 0xffff0000, v41
	s_waitcnt vmcnt(7)
	v_lshlrev_b32_e32 v2, 16, v30
	v_and_b32_e32 v30, 0xffff0000, v30
	v_lshlrev_b32_e32 v46, 16, v31
	v_and_b32_e32 v31, 0xffff0000, v31
	v_lshlrev_b32_e32 v47, 16, v32
	v_and_b32_e32 v32, 0xffff0000, v32
	v_lshlrev_b32_e32 v48, 16, v33
	v_and_b32_e32 v33, 0xffff0000, v33
	v_mul_f32_e32 v51, 0xbfb8aa3b, v30
	v_mul_f32_e32 v50, 0xbfb8aa3b, v2
	v_mul_f32_e32 v53, 0xbfb8aa3b, v31
	v_mul_f32_e32 v55, 0xbfb8aa3b, v32
	v_mul_f32_e32 v57, 0xbfb8aa3b, v33
	v_exp_f32_e32 v51, v51
	v_mul_f32_e32 v52, 0xbfb8aa3b, v46
	v_mul_f32_e32 v54, 0xbfb8aa3b, v47
	v_mul_f32_e32 v56, 0xbfb8aa3b, v48
	v_exp_f32_e32 v50, v50
	v_exp_f32_e32 v53, v53
	v_exp_f32_e32 v55, v55
	v_exp_f32_e32 v57, v57
	v_exp_f32_e32 v52, v52
	v_exp_f32_e32 v54, v54
	v_exp_f32_e32 v56, v56
	v_add_f32_e32 v51, 1.0, v51
	v_add_f32_e32 v50, 1.0, v50
	v_add_f32_e32 v53, 1.0, v53
	v_add_f32_e32 v55, 1.0, v55
	v_add_f32_e32 v57, 1.0, v57
	v_rcp_f32_e32 v51, v51
	v_add_f32_e32 v52, 1.0, v52
	v_add_f32_e32 v54, 1.0, v54
	v_add_f32_e32 v56, 1.0, v56
	v_rcp_f32_e32 v50, v50
	v_rcp_f32_e32 v53, v53
	v_rcp_f32_e32 v55, v55
	v_rcp_f32_e32 v57, v57
	v_rcp_f32_e32 v52, v52
	v_rcp_f32_e32 v54, v54
	v_rcp_f32_e32 v56, v56
	v_mul_f32_e32 v30, v51, v30
	v_mul_f32_e32 v2, v50, v2
	v_mul_f32_e32 v31, v53, v31
	v_mul_f32_e32 v32, v55, v32
	v_mul_f32_e32 v33, v57, v33
	v_mul_f32_e32 v30, v30, v38
	s_waitcnt vmcnt(6)
	v_lshlrev_b32_e32 v49, 16, v34
	v_mul_f32_e32 v46, v52, v46
	v_mul_f32_e32 v47, v54, v47
	v_mul_f32_e32 v48, v56, v48
	v_mul_f32_e32 v2, v2, v42
	v_mul_f32_e32 v31, v31, v39
	v_mul_f32_e32 v32, v32, v40
	v_mul_f32_e32 v33, v33, v41
	v_cvt_pk_bf16_f32 v30, v2, v30
	v_mul_f32_e32 v58, 0xbfb8aa3b, v49
	v_mul_f32_e32 v38, v46, v43
	v_mul_f32_e32 v39, v47, v44
	v_mul_f32_e32 v40, v48, v45
	v_cvt_pk_bf16_f32 v31, v38, v31
	v_cvt_pk_bf16_f32 v32, v39, v32
	v_cvt_pk_bf16_f32 v33, v40, v33
	global_store_dwordx4 v[28:29], v[30:33], off offset:1024
	v_exp_f32_e32 v2, v58
	ds_read_b128 v[38:41], v1 offset:16
	v_and_b32_e32 v30, 0xffff0000, v34
	v_mul_f32_e32 v31, 0xbfb8aa3b, v30
	v_exp_f32_e32 v31, v31
	v_add_f32_e32 v2, 1.0, v2
	v_rcp_f32_e32 v2, v2
	s_waitcnt lgkmcnt(0)
	v_lshlrev_b32_e32 v32, 16, v38
	v_add_f32_e32 v31, 1.0, v31
	v_rcp_f32_e32 v31, v31
	v_mul_f32_e32 v2, v2, v49
	v_mul_f32_e32 v2, v2, v32
	v_and_b32_e32 v32, 0xffff0000, v38
	v_mul_f32_e32 v30, v31, v30
	v_mul_f32_e32 v30, v30, v32
	v_cvt_pk_bf16_f32 v30, v2, v30
	v_lshlrev_b32_e32 v2, 16, v35
	v_and_b32_e32 v32, 0xffff0000, v35
	v_mul_f32_e32 v31, 0xbfb8aa3b, v2
	v_mul_f32_e32 v33, 0xbfb8aa3b, v32
	v_exp_f32_e32 v31, v31
	v_exp_f32_e32 v33, v33
	v_lshlrev_b32_e32 v34, 16, v39
	v_lshlrev_b32_e32 v35, 16, v40
	v_add_f32_e32 v31, 1.0, v31
	v_add_f32_e32 v33, 1.0, v33
	v_rcp_f32_e32 v31, v31
	v_rcp_f32_e32 v33, v33
	v_mul_f32_e32 v2, v31, v2
	v_and_b32_e32 v31, 0xffff0000, v39
	v_mul_f32_e32 v32, v33, v32
	v_mul_f32_e32 v2, v2, v34
	v_mul_f32_e32 v31, v32, v31
	v_cvt_pk_bf16_f32 v31, v2, v31
	v_lshlrev_b32_e32 v2, 16, v36
	v_and_b32_e32 v33, 0xffff0000, v36
	v_mul_f32_e32 v32, 0xbfb8aa3b, v2
	v_mul_f32_e32 v34, 0xbfb8aa3b, v33
	v_exp_f32_e32 v32, v32
	v_exp_f32_e32 v34, v34
	v_lshlrev_b32_e32 v36, 16, v41
	v_add_f32_e32 v32, 1.0, v32
	v_add_f32_e32 v34, 1.0, v34
	v_rcp_f32_e32 v32, v32
	v_rcp_f32_e32 v34, v34
	v_mul_f32_e32 v2, v32, v2
	v_and_b32_e32 v32, 0xffff0000, v40
	v_mul_f32_e32 v33, v34, v33
	v_mul_f32_e32 v2, v2, v35
	v_mul_f32_e32 v32, v33, v32
	v_cvt_pk_bf16_f32 v32, v2, v32
	v_lshlrev_b32_e32 v2, 16, v37
	v_and_b32_e32 v34, 0xffff0000, v37
	v_mul_f32_e32 v33, 0xbfb8aa3b, v2
	v_mul_f32_e32 v35, 0xbfb8aa3b, v34
	v_exp_f32_e32 v33, v33
	v_exp_f32_e32 v35, v35
	v_add_f32_e32 v33, 1.0, v33
	v_add_f32_e32 v35, 1.0, v35
	v_rcp_f32_e32 v33, v33
	v_rcp_f32_e32 v35, v35
	v_mul_f32_e32 v2, v33, v2
	v_and_b32_e32 v33, 0xffff0000, v41
	v_mul_f32_e32 v34, v35, v34
	v_mul_f32_e32 v2, v2, v36
	v_mul_f32_e32 v33, v34, v33
	v_cvt_pk_bf16_f32 v33, v2, v33
	s_waitcnt vmcnt(5)
; #define LAS __attribute__((address_space(3)))
; __device__ __forceinline__ unsigned cvtpk(float lo, float hi) { unsigned r; asm volatile("v_cvt_pk_bf16_f32 %0, %1, %2" : "=v"(r) : "v"(lo), "v"(hi)); return r; }
; __device__ __forceinline__ float bf_lo(unsigned w) { return __uint_as_float(w << 16); }
; __device__ __forceinline__ float bf_hi(unsigned w) { return __uint_as_float(w & 0xffff0000u); }
; __device__ __forceinline__ float fast_exp2(float x) { return __builtin_amdgcn_exp2f(x); }
; __device__ __forceinline__ float fast_rcp(float x) { return __builtin_amdgcn_rcpf(x); }
; __device__ __forceinline__ float silu_f(float x) { return x * fast_rcp(1.f + fast_exp2(-x * LOG2E)); }
; template <int MODE> ...
;     ...
;             for (int j = 0; j < 8; ++j) { const u32x4 ov = *(const LAS u32x4*)(ost + (lane >> 1) * 272 + (c0 + 8 * j) * 2); u32x4 w;
; #pragma unroll
;                 for (int e = 0; e < 4; ++e) w[e] = cvtpk(bf_lo(ov[e]) * silu_f(bf_lo(gv[j][e])), bf_hi(ov[e]) * silu_f(bf_hi(gv[j][e])));
;                 *(u32x4*)(op + 8 * j) = w; }
	v_lshlrev_b32_e32 v2, 16, v24
	v_and_b32_e32 v24, 0xffff0000, v24
	v_mul_f32_e32 v34, 0xbfb8aa3b, v2
	v_mul_f32_e32 v35, 0xbfb8aa3b, v24
	v_exp_f32_e32 v34, v34
	v_exp_f32_e32 v35, v35
	global_store_dwordx4 v[28:29], v[30:33], off offset:1040
	ds_read_b128 v[30:33], v1 offset:32
	v_add_f32_e32 v34, 1.0, v34
	v_add_f32_e32 v35, 1.0, v35
	v_rcp_f32_e32 v34, v34
	v_rcp_f32_e32 v35, v35
	s_waitcnt lgkmcnt(0)
	v_lshlrev_b32_e32 v36, 16, v30
	v_and_b32_e32 v30, 0xffff0000, v30
	v_mul_f32_e32 v2, v34, v2
	v_mul_f32_e32 v24, v35, v24
	v_mul_f32_e32 v2, v2, v36
	v_mul_f32_e32 v24, v24, v30
	v_cvt_pk_bf16_f32 v24, v2, v24
	v_lshlrev_b32_e32 v2, 16, v25
	v_and_b32_e32 v25, 0xffff0000, v25
	v_mul_f32_e32 v30, 0xbfb8aa3b, v2
	v_mul_f32_e32 v34, 0xbfb8aa3b, v25
	v_exp_f32_e32 v30, v30
	v_exp_f32_e32 v34, v34
	v_lshlrev_b32_e32 v35, 16, v31
	v_add_f32_e32 v30, 1.0, v30
	v_add_f32_e32 v34, 1.0, v34
	v_rcp_f32_e32 v30, v30
	v_rcp_f32_e32 v34, v34
	v_mul_f32_e32 v2, v30, v2
	v_and_b32_e32 v30, 0xffff0000, v31
	v_mul_f32_e32 v25, v34, v25
	v_mul_f32_e32 v2, v2, v35
	v_mul_f32_e32 v25, v25, v30
	v_cvt_pk_bf16_f32 v25, v2, v25
	v_lshlrev_b32_e32 v2, 16, v26
	v_and_b32_e32 v26, 0xffff0000, v26
	v_mul_f32_e32 v30, 0xbfb8aa3b, v2
	v_mul_f32_e32 v31, 0xbfb8aa3b, v26
	v_exp_f32_e32 v30, v30
	v_exp_f32_e32 v31, v31
	v_lshlrev_b32_e32 v34, 16, v32
	v_add_f32_e32 v30, 1.0, v30
	v_add_f32_e32 v31, 1.0, v31
	v_rcp_f32_e32 v30, v30
	v_rcp_f32_e32 v31, v31
	v_mul_f32_e32 v2, v30, v2
	v_and_b32_e32 v30, 0xffff0000, v32
	v_mul_f32_e32 v26, v31, v26
	v_mul_f32_e32 v2, v2, v34
	v_mul_f32_e32 v26, v26, v30
	v_cvt_pk_bf16_f32 v26, v2, v26
	v_lshlrev_b32_e32 v2, 16, v27
	v_and_b32_e32 v27, 0xffff0000, v27
	v_mul_f32_e32 v30, 0xbfb8aa3b, v2
	v_mul_f32_e32 v31, 0xbfb8aa3b, v27
	v_exp_f32_e32 v30, v30
	v_exp_f32_e32 v31, v31
	v_lshlrev_b32_e32 v32, 16, v33
	v_add_f32_e32 v30, 1.0, v30
	v_add_f32_e32 v31, 1.0, v31
	v_rcp_f32_e32 v30, v30
	v_rcp_f32_e32 v31, v31
	v_mul_f32_e32 v2, v30, v2
	v_and_b32_e32 v30, 0xffff0000, v33
	v_mul_f32_e32 v27, v31, v27
	v_mul_f32_e32 v2, v2, v32
	v_mul_f32_e32 v27, v27, v30
	v_cvt_pk_bf16_f32 v27, v2, v27
	v_lshlrev_b32_e32 v2, 16, v20
	v_and_b32_e32 v20, 0xffff0000, v20
	v_mul_f32_e32 v30, 0xbfb8aa3b, v2
	v_mul_f32_e32 v31, 0xbfb8aa3b, v20
	v_exp_f32_e32 v30, v30
	v_exp_f32_e32 v31, v31
	global_store_dwordx4 v[28:29], v[24:27], off offset:1056
	ds_read_b128 v[24:27], v1 offset:48
	v_add_f32_e32 v30, 1.0, v30
	v_add_f32_e32 v31, 1.0, v31
	v_rcp_f32_e32 v30, v30
	v_rcp_f32_e32 v31, v31
	s_waitcnt lgkmcnt(0)
	v_lshlrev_b32_e32 v32, 16, v24
	v_and_b32_e32 v24, 0xffff0000, v24
	v_mul_f32_e32 v2, v30, v2
	v_mul_f32_e32 v20, v31, v20
	v_mul_f32_e32 v2, v2, v32
	v_mul_f32_e32 v20, v20, v24
	v_cvt_pk_bf16_f32 v20, v2, v20
	v_lshlrev_b32_e32 v2, 16, v21
	v_and_b32_e32 v21, 0xffff0000, v21
	v_mul_f32_e32 v24, 0xbfb8aa3b, v2
	v_mul_f32_e32 v30, 0xbfb8aa3b, v21
	v_exp_f32_e32 v24, v24
	v_exp_f32_e32 v30, v30
	v_lshlrev_b32_e32 v31, 16, v25
	v_add_f32_e32 v24, 1.0, v24
	v_add_f32_e32 v30, 1.0, v30
	v_rcp_f32_e32 v24, v24
	v_rcp_f32_e32 v30, v30
	v_mul_f32_e32 v2, v24, v2
	v_and_b32_e32 v24, 0xffff0000, v25
	v_mul_f32_e32 v21, v30, v21
	v_mul_f32_e32 v2, v2, v31
	v_mul_f32_e32 v21, v21, v24
	v_cvt_pk_bf16_f32 v21, v2, v21
	v_lshlrev_b32_e32 v2, 16, v22
	v_and_b32_e32 v22, 0xffff0000, v22
	v_mul_f32_e32 v24, 0xbfb8aa3b, v2
	v_mul_f32_e32 v25, 0xbfb8aa3b, v22
	v_exp_f32_e32 v24, v24
	v_exp_f32_e32 v25, v25
	v_lshlrev_b32_e32 v30, 16, v26
	v_add_f32_e32 v24, 1.0, v24
	v_add_f32_e32 v25, 1.0, v25
	v_rcp_f32_e32 v24, v24
	v_rcp_f32_e32 v25, v25
	v_mul_f32_e32 v2, v24, v2
	v_and_b32_e32 v24, 0xffff0000, v26
	v_mul_f32_e32 v22, v25, v22
	v_mul_f32_e32 v2, v2, v30
	v_mul_f32_e32 v22, v22, v24
	v_cvt_pk_bf16_f32 v22, v2, v22
	v_lshlrev_b32_e32 v2, 16, v23
	v_and_b32_e32 v23, 0xffff0000, v23
	v_mul_f32_e32 v24, 0xbfb8aa3b, v2
	v_mul_f32_e32 v25, 0xbfb8aa3b, v23
	v_exp_f32_e32 v24, v24
	v_exp_f32_e32 v25, v25
	v_lshlrev_b32_e32 v26, 16, v27
	v_add_f32_e32 v24, 1.0, v24
	v_add_f32_e32 v25, 1.0, v25
	v_rcp_f32_e32 v24, v24
	v_rcp_f32_e32 v25, v25
	v_mul_f32_e32 v2, v24, v2
	v_and_b32_e32 v24, 0xffff0000, v27
	v_mul_f32_e32 v23, v25, v23
	v_mul_f32_e32 v2, v2, v26
	v_mul_f32_e32 v23, v23, v24
	v_cvt_pk_bf16_f32 v23, v2, v23
	s_waitcnt vmcnt(3)
	v_lshlrev_b32_e32 v2, 16, v16
	v_and_b32_e32 v16, 0xffff0000, v16
	v_mul_f32_e32 v24, 0xbfb8aa3b, v2
	v_mul_f32_e32 v25, 0xbfb8aa3b, v16
	v_exp_f32_e32 v24, v24
	v_exp_f32_e32 v25, v25
	global_store_dwordx4 v[28:29], v[20:23], off offset:1072
	ds_read_b128 v[20:23], v1 offset:64
	v_add_f32_e32 v24, 1.0, v24
	v_add_f32_e32 v25, 1.0, v25
	v_rcp_f32_e32 v24, v24
	v_rcp_f32_e32 v25, v25
	s_waitcnt lgkmcnt(0)
; #define LAS __attribute__((address_space(3)))
; __device__ __forceinline__ unsigned cvtpk(float lo, float hi) { unsigned r; asm volatile("v_cvt_pk_bf16_f32 %0, %1, %2" : "=v"(r) : "v"(lo), "v"(hi)); return r; }
; __device__ __forceinline__ float bf_lo(unsigned w) { return __uint_as_float(w << 16); }
; __device__ __forceinline__ float bf_hi(unsigned w) { return __uint_as_float(w & 0xffff0000u); }
; __device__ __forceinline__ float fast_exp2(float x) { return __builtin_amdgcn_exp2f(x); }
; __device__ __forceinline__ float fast_rcp(float x) { return __builtin_amdgcn_rcpf(x); }
; __device__ __forceinline__ float silu_f(float x) { return x * fast_rcp(1.f + fast_exp2(-x * LOG2E)); }
; template <int MODE> ...
;     ...
;             for (int j = 0; j < 8; ++j) { const u32x4 ov = *(const LAS u32x4*)(ost + (lane >> 1) * 272 + (c0 + 8 * j) * 2); u32x4 w;
; #pragma unroll
;                 for (int e = 0; e < 4; ++e) w[e] = cvtpk(bf_lo(ov[e]) * silu_f(bf_lo(gv[j][e])), bf_hi(ov[e]) * silu_f(bf_hi(gv[j][e])));
;                 *(u32x4*)(op + 8 * j) = w; }
	v_lshlrev_b32_e32 v26, 16, v20
	v_and_b32_e32 v20, 0xffff0000, v20
	v_mul_f32_e32 v2, v24, v2
	v_mul_f32_e32 v16, v25, v16
	v_mul_f32_e32 v2, v2, v26
	v_mul_f32_e32 v16, v16, v20
	v_cvt_pk_bf16_f32 v16, v2, v16
	v_lshlrev_b32_e32 v2, 16, v17
	v_and_b32_e32 v17, 0xffff0000, v17
	v_mul_f32_e32 v20, 0xbfb8aa3b, v2
	v_mul_f32_e32 v24, 0xbfb8aa3b, v17
	v_exp_f32_e32 v20, v20
	v_exp_f32_e32 v24, v24
	v_lshlrev_b32_e32 v25, 16, v21
	v_add_f32_e32 v20, 1.0, v20
	v_add_f32_e32 v24, 1.0, v24
	v_rcp_f32_e32 v20, v20
	v_rcp_f32_e32 v24, v24
	v_mul_f32_e32 v2, v20, v2
	v_and_b32_e32 v20, 0xffff0000, v21
	v_mul_f32_e32 v17, v24, v17
	v_mul_f32_e32 v2, v2, v25
	v_mul_f32_e32 v17, v17, v20
	v_cvt_pk_bf16_f32 v17, v2, v17
	v_lshlrev_b32_e32 v2, 16, v18
	v_and_b32_e32 v18, 0xffff0000, v18
	v_mul_f32_e32 v20, 0xbfb8aa3b, v2
	v_mul_f32_e32 v21, 0xbfb8aa3b, v18
	v_exp_f32_e32 v20, v20
	v_exp_f32_e32 v21, v21
	v_lshlrev_b32_e32 v24, 16, v22
	v_add_f32_e32 v20, 1.0, v20
	v_add_f32_e32 v21, 1.0, v21
	v_rcp_f32_e32 v20, v20
	v_rcp_f32_e32 v21, v21
	v_mul_f32_e32 v2, v20, v2
	v_and_b32_e32 v20, 0xffff0000, v22
	v_mul_f32_e32 v18, v21, v18
	v_mul_f32_e32 v2, v2, v24
	v_mul_f32_e32 v18, v18, v20
	v_cvt_pk_bf16_f32 v18, v2, v18
	v_lshlrev_b32_e32 v2, 16, v19
	v_and_b32_e32 v19, 0xffff0000, v19
	v_mul_f32_e32 v20, 0xbfb8aa3b, v2
	v_mul_f32_e32 v21, 0xbfb8aa3b, v19
	v_exp_f32_e32 v20, v20
	v_exp_f32_e32 v21, v21
	v_lshlrev_b32_e32 v22, 16, v23
	v_add_f32_e32 v20, 1.0, v20
	v_add_f32_e32 v21, 1.0, v21
	v_rcp_f32_e32 v20, v20
	v_rcp_f32_e32 v21, v21
	v_mul_f32_e32 v2, v20, v2
	v_and_b32_e32 v20, 0xffff0000, v23
	v_mul_f32_e32 v19, v21, v19
	v_mul_f32_e32 v2, v2, v22
	v_mul_f32_e32 v19, v19, v20
	v_cvt_pk_bf16_f32 v19, v2, v19
	v_lshlrev_b32_e32 v2, 16, v12
	v_and_b32_e32 v12, 0xffff0000, v12
	v_mul_f32_e32 v20, 0xbfb8aa3b, v2
	v_mul_f32_e32 v21, 0xbfb8aa3b, v12
	v_exp_f32_e32 v20, v20
	v_exp_f32_e32 v21, v21
	global_store_dwordx4 v[28:29], v[16:19], off offset:1088
	ds_read_b128 v[16:19], v1 offset:80
	v_add_f32_e32 v20, 1.0, v20
	v_add_f32_e32 v21, 1.0, v21
	v_rcp_f32_e32 v20, v20
	v_rcp_f32_e32 v21, v21
	s_waitcnt lgkmcnt(0)
	v_lshlrev_b32_e32 v22, 16, v16
	v_and_b32_e32 v16, 0xffff0000, v16
	v_mul_f32_e32 v2, v20, v2
	v_mul_f32_e32 v12, v21, v12
	v_mul_f32_e32 v2, v2, v22
	v_mul_f32_e32 v12, v12, v16
	v_cvt_pk_bf16_f32 v12, v2, v12
	v_lshlrev_b32_e32 v2, 16, v13
	v_and_b32_e32 v13, 0xffff0000, v13
	v_mul_f32_e32 v16, 0xbfb8aa3b, v2
	v_mul_f32_e32 v20, 0xbfb8aa3b, v13
	v_exp_f32_e32 v16, v16
	v_exp_f32_e32 v20, v20
	v_lshlrev_b32_e32 v21, 16, v17
	v_add_f32_e32 v16, 1.0, v16
	v_add_f32_e32 v20, 1.0, v20
	v_rcp_f32_e32 v16, v16
	v_rcp_f32_e32 v20, v20
	v_mul_f32_e32 v2, v16, v2
	v_and_b32_e32 v16, 0xffff0000, v17
	v_mul_f32_e32 v13, v20, v13
	v_mul_f32_e32 v2, v2, v21
	v_mul_f32_e32 v13, v13, v16
	v_cvt_pk_bf16_f32 v13, v2, v13
	v_lshlrev_b32_e32 v2, 16, v14
	v_and_b32_e32 v14, 0xffff0000, v14
	v_mul_f32_e32 v16, 0xbfb8aa3b, v2
	v_mul_f32_e32 v17, 0xbfb8aa3b, v14
	v_exp_f32_e32 v16, v16
	v_exp_f32_e32 v17, v17
	v_lshlrev_b32_e32 v20, 16, v18
	v_add_f32_e32 v16, 1.0, v16
	v_add_f32_e32 v17, 1.0, v17
	v_rcp_f32_e32 v16, v16
	v_rcp_f32_e32 v17, v17
	v_mul_f32_e32 v2, v16, v2
	v_and_b32_e32 v16, 0xffff0000, v18
	v_mul_f32_e32 v14, v17, v14
	v_mul_f32_e32 v2, v2, v20
	v_mul_f32_e32 v14, v14, v16
	v_cvt_pk_bf16_f32 v14, v2, v14
	v_lshlrev_b32_e32 v2, 16, v15
	v_and_b32_e32 v15, 0xffff0000, v15
	v_mul_f32_e32 v16, 0xbfb8aa3b, v2
	v_mul_f32_e32 v17, 0xbfb8aa3b, v15
	v_exp_f32_e32 v16, v16
	v_exp_f32_e32 v17, v17
	v_lshlrev_b32_e32 v18, 16, v19
	v_add_f32_e32 v16, 1.0, v16
	v_add_f32_e32 v17, 1.0, v17
	v_rcp_f32_e32 v16, v16
	v_rcp_f32_e32 v17, v17
	v_mul_f32_e32 v2, v16, v2
	v_and_b32_e32 v16, 0xffff0000, v19
	v_mul_f32_e32 v15, v17, v15
	v_mul_f32_e32 v2, v2, v18
	v_mul_f32_e32 v15, v15, v16
	v_cvt_pk_bf16_f32 v15, v2, v15
	v_lshlrev_b32_e32 v2, 16, v8
	v_and_b32_e32 v8, 0xffff0000, v8
	v_mul_f32_e32 v16, 0xbfb8aa3b, v2
	v_mul_f32_e32 v17, 0xbfb8aa3b, v8
	v_exp_f32_e32 v16, v16
	v_exp_f32_e32 v17, v17
	global_store_dwordx4 v[28:29], v[12:15], off offset:1104
	ds_read_b128 v[12:15], v1 offset:96
	v_add_f32_e32 v16, 1.0, v16
	v_add_f32_e32 v17, 1.0, v17
	v_rcp_f32_e32 v16, v16
	v_rcp_f32_e32 v17, v17
	s_waitcnt lgkmcnt(0)
; #define LAS __attribute__((address_space(3)))
; __device__ __forceinline__ unsigned cvtpk(float lo, float hi) { unsigned r; asm volatile("v_cvt_pk_bf16_f32 %0, %1, %2" : "=v"(r) : "v"(lo), "v"(hi)); return r; }
; __device__ __forceinline__ float bf_lo(unsigned w) { return __uint_as_float(w << 16); }
; __device__ __forceinline__ float bf_hi(unsigned w) { return __uint_as_float(w & 0xffff0000u); }
; __device__ __forceinline__ float fast_exp2(float x) { return __builtin_amdgcn_exp2f(x); }
; __device__ __forceinline__ float fast_rcp(float x) { return __builtin_amdgcn_rcpf(x); }
; __device__ __forceinline__ float silu_f(float x) { return x * fast_rcp(1.f + fast_exp2(-x * LOG2E)); }
; template <int MODE> ...
;     ...
;             for (int j = 0; j < 8; ++j) { const u32x4 ov = *(const LAS u32x4*)(ost + (lane >> 1) * 272 + (c0 + 8 * j) * 2); u32x4 w;
; #pragma unroll
;                 for (int e = 0; e < 4; ++e) w[e] = cvtpk(bf_lo(ov[e]) * silu_f(bf_lo(gv[j][e])), bf_hi(ov[e]) * silu_f(bf_hi(gv[j][e])));
;                 *(u32x4*)(op + 8 * j) = w; }
	v_lshlrev_b32_e32 v18, 16, v12
	v_and_b32_e32 v12, 0xffff0000, v12
	v_mul_f32_e32 v2, v16, v2
	v_mul_f32_e32 v8, v17, v8
	v_mul_f32_e32 v2, v2, v18
	v_mul_f32_e32 v8, v8, v12
	v_cvt_pk_bf16_f32 v8, v2, v8
	v_lshlrev_b32_e32 v2, 16, v9
	v_and_b32_e32 v9, 0xffff0000, v9
	v_mul_f32_e32 v12, 0xbfb8aa3b, v2
	v_mul_f32_e32 v16, 0xbfb8aa3b, v9
	v_exp_f32_e32 v12, v12
	v_exp_f32_e32 v16, v16
	v_lshlrev_b32_e32 v17, 16, v13
	v_add_f32_e32 v12, 1.0, v12
	v_add_f32_e32 v16, 1.0, v16
	v_rcp_f32_e32 v12, v12
	v_rcp_f32_e32 v16, v16
	v_mul_f32_e32 v2, v12, v2
	v_and_b32_e32 v12, 0xffff0000, v13
	v_mul_f32_e32 v9, v16, v9
	v_mul_f32_e32 v2, v2, v17
	v_mul_f32_e32 v9, v9, v12
	v_cvt_pk_bf16_f32 v9, v2, v9
	v_lshlrev_b32_e32 v2, 16, v10
	v_and_b32_e32 v10, 0xffff0000, v10
	v_mul_f32_e32 v12, 0xbfb8aa3b, v2
	v_mul_f32_e32 v13, 0xbfb8aa3b, v10
	v_exp_f32_e32 v12, v12
	v_exp_f32_e32 v13, v13
	v_lshlrev_b32_e32 v16, 16, v14
	v_add_f32_e32 v12, 1.0, v12
	v_add_f32_e32 v13, 1.0, v13
	v_rcp_f32_e32 v12, v12
	v_rcp_f32_e32 v13, v13
	v_mul_f32_e32 v2, v12, v2
	v_and_b32_e32 v12, 0xffff0000, v14
	v_mul_f32_e32 v10, v13, v10
	v_mul_f32_e32 v2, v2, v16
	v_mul_f32_e32 v10, v10, v12
	v_cvt_pk_bf16_f32 v10, v2, v10
	v_lshlrev_b32_e32 v2, 16, v11
	v_and_b32_e32 v11, 0xffff0000, v11
	v_mul_f32_e32 v12, 0xbfb8aa3b, v2
	v_mul_f32_e32 v13, 0xbfb8aa3b, v11
	v_exp_f32_e32 v12, v12
	v_exp_f32_e32 v13, v13
	v_lshlrev_b32_e32 v14, 16, v15
	v_add_f32_e32 v12, 1.0, v12
	v_add_f32_e32 v13, 1.0, v13
	v_rcp_f32_e32 v12, v12
	v_rcp_f32_e32 v13, v13
	v_mul_f32_e32 v2, v12, v2
	v_and_b32_e32 v12, 0xffff0000, v15
	v_mul_f32_e32 v11, v13, v11
	v_mul_f32_e32 v11, v11, v12
	v_mul_f32_e32 v2, v2, v14
	v_cvt_pk_bf16_f32 v11, v2, v11
	global_store_dwordx4 v[28:29], v[8:11], off offset:1120
	ds_read_b128 v[8:11], v1 offset:112
	v_lshlrev_b32_e32 v1, 16, v4
	v_mul_f32_e32 v2, 0xbfb8aa3b, v1
	v_and_b32_e32 v4, 0xffff0000, v4
	v_exp_f32_e32 v2, v2
	v_mul_f32_e32 v12, 0xbfb8aa3b, v4
	v_exp_f32_e32 v12, v12
	s_waitcnt lgkmcnt(0)
	v_lshlrev_b32_e32 v13, 16, v8
	v_add_f32_e32 v2, 1.0, v2
	v_rcp_f32_e32 v2, v2
	v_add_f32_e32 v12, 1.0, v12
	v_rcp_f32_e32 v12, v12
	v_mul_f32_e32 v1, v2, v1
	v_mul_f32_e32 v1, v1, v13
	v_and_b32_e32 v2, 0xffff0000, v8
	v_mul_f32_e32 v4, v12, v4
	v_mul_f32_e32 v2, v4, v2
	v_cvt_pk_bf16_f32 v4, v1, v2
	v_lshlrev_b32_e32 v1, 16, v5
	v_mul_f32_e32 v2, 0xbfb8aa3b, v1
	v_and_b32_e32 v5, 0xffff0000, v5
	v_exp_f32_e32 v2, v2
	v_mul_f32_e32 v8, 0xbfb8aa3b, v5
	v_exp_f32_e32 v8, v8
	v_lshlrev_b32_e32 v12, 16, v9
	v_add_f32_e32 v2, 1.0, v2
	v_rcp_f32_e32 v2, v2
	v_add_f32_e32 v8, 1.0, v8
	v_rcp_f32_e32 v8, v8
	v_mul_f32_e32 v1, v2, v1
	v_mul_f32_e32 v1, v1, v12
	v_and_b32_e32 v2, 0xffff0000, v9
	v_mul_f32_e32 v5, v8, v5
	v_mul_f32_e32 v2, v5, v2
	v_cvt_pk_bf16_f32 v5, v1, v2
	v_lshlrev_b32_e32 v1, 16, v6
	v_mul_f32_e32 v2, 0xbfb8aa3b, v1
	v_and_b32_e32 v6, 0xffff0000, v6
	v_exp_f32_e32 v2, v2
	v_mul_f32_e32 v8, 0xbfb8aa3b, v6
	v_exp_f32_e32 v8, v8
	v_lshlrev_b32_e32 v9, 16, v10
	v_add_f32_e32 v2, 1.0, v2
	v_rcp_f32_e32 v2, v2
	v_add_f32_e32 v8, 1.0, v8
	v_rcp_f32_e32 v8, v8
	v_mul_f32_e32 v1, v2, v1
	v_mul_f32_e32 v1, v1, v9
	v_and_b32_e32 v2, 0xffff0000, v10
	v_mul_f32_e32 v6, v8, v6
	v_mul_f32_e32 v2, v6, v2
	v_cvt_pk_bf16_f32 v6, v1, v2
	v_lshlrev_b32_e32 v1, 16, v7
	v_and_b32_e32 v7, 0xffff0000, v7
	v_mul_f32_e32 v2, 0xbfb8aa3b, v1
	v_mul_f32_e32 v8, 0xbfb8aa3b, v7
	v_exp_f32_e32 v2, v2
	v_exp_f32_e32 v8, v8
	v_lshlrev_b32_e32 v9, 16, v11
	v_add_f32_e32 v2, 1.0, v2
	v_add_f32_e32 v8, 1.0, v8
	v_rcp_f32_e32 v2, v2
	v_rcp_f32_e32 v8, v8
	v_mul_f32_e32 v1, v2, v1
	v_and_b32_e32 v2, 0xffff0000, v11
	v_mul_f32_e32 v7, v8, v7
	v_mul_f32_e32 v1, v1, v9
	v_mul_f32_e32 v2, v7, v2
	v_cvt_pk_bf16_f32 v7, v1, v2
	global_store_dwordx4 v[28:29], v[4:7], off offset:1136
	s_branch .LBB0_837
